# MLA PV: second V block's fragment reads issued before the first PV MFMA (one more MFMA of LDS latency cover, counted waits 14..0); on top of zero-once + MLA K read-ahead
# speedup vs baseline: 1.0004x; 1.0004x over previous
; __device__ __forceinline__ s16x4 vtr(const LAS unsigned char* p) { return __builtin_bit_cast(s16x4, __builtin_amdgcn_ds_read_tr16_b64_v4i16((LAS v4i16_t*)p)); }
; template <int DQK, int DV, bool HAS_BIAS>
; __device__ __forceinline__ void attn_tile(AttnState<DQK, DV>& st, const LAS unsigned char* Kt, const LAS unsigned char* Vt, int bias_mode, const LAS float* tab, int rel0, int nkeys, bool first, LAS float* wsf, int lane) {
;     ...
;     float sum0 = 0.f, sum1 = 0.f;
; #pragma unroll
;     for (int r = 0; r < 16; ++r) { p0[r] = __builtin_amdgcn_exp2f(p0[r]); p1[r] = __builtin_amdgcn_exp2f(p1[r]); sum0 += p0[r]; sum1 += p1[r]; }
;     st.l += sum0 + sum1;
;     bf16x8 pf[4];
;     pf[0] = pack8(p0[0], p0[1], p0[2], p0[3], p0[4], p0[5], p0[6], p0[7]);
;     pf[1] = pack8(p0[8], p0[9], p0[10], p0[11], p0[12], p0[13], p0[14], p0[15]);
;     pf[2] = pack8(p1[0], p1[1], p1[2], p1[3], p1[4], p1[5], p1[6], p1[7]);
;     pf[3] = pack8(p1[8], p1[9], p1[10], p1[11], p1[12], p1[13], p1[14], p1[15]);
;     __builtin_amdgcn_sched_barrier(0);
; #pragma unroll
;     for (int db = 0; db < NDB; ++db) {
;         if (db + 1 < NDB) {
; #pragma unroll
;             for (int s4 = 0; s4 < 4; ++s4) { vlo[(db + 1) & 1][s4] = vtr(vp + (16 * s4) * PV + (db + 1) * 64); vhi[(db + 1) & 1][s4] = vtr(vp + (16 * s4 + 8) * PV + (db + 1) * 64); }
;         }
; #pragma unroll
;         for (int s4 = 0; s4 < 4; ++s4) {
;             const s16x4 lo = vlo[db & 1][s4], h4 = vhi[db & 1][s4];
;             const bf16x8 vb = {lo[0], lo[1], lo[2], lo[3], h4[0], h4[1], h4[2], h4[3]};
;             st.o[db] = __builtin_amdgcn_mfma_f32_32x32x16_bf16(pf[s4], vb, st.o[db], 0, 0, 0);
;         }
;         __builtin_amdgcn_sched_barrier(0);
;     }
.LBB0_589:
	v_exp_f32_e32 v151, v48
	v_exp_f32_e32 v150, v64
	v_exp_f32_e32 v165, v49
	v_exp_f32_e32 v164, v65
	v_exp_f32_e32 v65, v50
	v_exp_f32_e32 v64, v66
	v_exp_f32_e32 v167, v51
	v_exp_f32_e32 v166, v67
	v_pk_add_f32 v[48:49], v[150:151], 0 op_sel_hi:[1,0]
	v_exp_f32_e32 v67, v52
	v_exp_f32_e32 v66, v68
	v_pk_add_f32 v[48:49], v[164:165], v[48:49]
	v_exp_f32_e32 v169, v53
	v_exp_f32_e32 v168, v69
	v_pk_add_f32 v[48:49], v[64:65], v[48:49]
	v_exp_f32_e32 v69, v54
	v_exp_f32_e32 v68, v70
	v_pk_add_f32 v[48:49], v[166:167], v[48:49]
	v_exp_f32_e32 v171, v55
	v_exp_f32_e32 v170, v71
	v_exp_f32_e32 v71, v56
	v_exp_f32_e32 v70, v72
	v_pk_add_f32 v[48:49], v[66:67], v[48:49]
	v_exp_f32_e32 v173, v57
	v_exp_f32_e32 v172, v73
	v_pk_add_f32 v[48:49], v[168:169], v[48:49]
	v_exp_f32_e32 v73, v58
	v_exp_f32_e32 v72, v74
	v_pk_add_f32 v[48:49], v[68:69], v[48:49]
	v_exp_f32_e32 v175, v59
	v_exp_f32_e32 v174, v75
	v_pk_add_f32 v[48:49], v[170:171], v[48:49]
	v_exp_f32_e32 v75, v60
	v_exp_f32_e32 v74, v76
	v_pk_add_f32 v[48:49], v[70:71], v[48:49]
	v_exp_f32_e32 v177, v61
	v_exp_f32_e32 v176, v77
	v_pk_add_f32 v[48:49], v[172:173], v[48:49]
	v_exp_f32_e32 v77, v62
	v_exp_f32_e32 v76, v78
	v_pk_add_f32 v[48:49], v[72:73], v[48:49]
	v_exp_f32_e32 v179, v63
	v_exp_f32_e32 v178, v79
	v_pk_add_f32 v[48:49], v[174:175], v[48:49]
	v_cvt_pk_bf16_f32 v50, v67, v169
	v_pk_add_f32 v[48:49], v[74:75], v[48:49]
	v_cvt_pk_bf16_f32 v51, v69, v171
	v_pk_add_f32 v[48:49], v[176:177], v[48:49]
	v_cvt_pk_bf16_f32 v52, v71, v173
	v_pk_add_f32 v[48:49], v[76:77], v[48:49]
	v_cvt_pk_bf16_f32 v53, v73, v175
	v_pk_add_f32 v[48:49], v[178:179], v[48:49]
	v_cvt_pk_bf16_f32 v54, v75, v177
	v_add_f32_e32 v48, v48, v49
	v_add_f32_e32 v160, v160, v48
	v_cvt_pk_bf16_f32 v48, v151, v165
	v_cvt_pk_bf16_f32 v49, v65, v167
	v_cvt_pk_bf16_f32 v55, v77, v179
	v_cvt_pk_bf16_f32 v56, v150, v164
	v_cvt_pk_bf16_f32 v57, v64, v166
	v_cvt_pk_bf16_f32 v58, v66, v168
	v_cvt_pk_bf16_f32 v59, v68, v170
	v_cvt_pk_bf16_f32 v60, v70, v172
	v_cvt_pk_bf16_f32 v61, v72, v174
	v_cvt_pk_bf16_f32 v62, v74, v176
	v_cvt_pk_bf16_f32 v63, v76, v178
	ds_read_b64_tr_b16 v[64:65], v163 offset:47168
	ds_read_b64_tr_b16 v[66:67], v163 offset:48704
	ds_read_b64_tr_b16 v[68:69], v163 offset:50240
	ds_read_b64_tr_b16 v[70:71], v163 offset:51776
	ds_read_b64_tr_b16 v[72:73], v163 offset:53312
	ds_read_b64_tr_b16 v[74:75], v163 offset:54848
	ds_read_b64_tr_b16 v[76:77], v163 offset:56384
	ds_read_b64_tr_b16 v[78:79], v163 offset:57920
	s_waitcnt lgkmcnt(14)
	v_mfma_f32_32x32x16_bf16 v[16:31], v[48:51], v[140:143], v[16:31]
	s_waitcnt lgkmcnt(12)
	v_mfma_f32_32x32x16_bf16 v[16:31], v[52:55], v[136:139], v[16:31]
	s_waitcnt lgkmcnt(10)
	v_mfma_f32_32x32x16_bf16 v[16:31], v[56:59], v[132:135], v[16:31]
	s_waitcnt lgkmcnt(8)
	v_mfma_f32_32x32x16_bf16 v[16:31], v[60:63], v[128:131], v[16:31]
	s_waitcnt lgkmcnt(6)
	v_mfma_f32_32x32x16_bf16 v[0:15], v[48:51], v[64:67], v[0:15]
	s_waitcnt lgkmcnt(4)
	v_mfma_f32_32x32x16_bf16 v[0:15], v[52:55], v[68:71], v[0:15]
	s_waitcnt lgkmcnt(2)
	v_mfma_f32_32x32x16_bf16 v[0:15], v[56:59], v[72:75], v[0:15]
	s_waitcnt lgkmcnt(0)
	v_mfma_f32_32x32x16_bf16 v[0:15], v[60:63], v[76:79], v[0:15]
	s_andn2_b64 vcc, exec, s[36:37]
	s_cbranch_vccnz .LBB0_593

; __device__ __forceinline__ s16x4 vtr(const LAS unsigned char* p) { return __builtin_bit_cast(s16x4, __builtin_amdgcn_ds_read_tr16_b64_v4i16((LAS v4i16_t*)p)); }
; template <int DQK, int DV, bool HAS_BIAS>
; __device__ __forceinline__ void attn_tile(AttnState<DQK, DV>& st, const LAS unsigned char* Kt, const LAS unsigned char* Vt, int bias_mode, const LAS float* tab, int rel0, int nkeys, bool first, LAS float* wsf, int lane) {
;     ...
;     float sum0 = 0.f, sum1 = 0.f;
; #pragma unroll
;     for (int r = 0; r < 16; ++r) { p0[r] = __builtin_amdgcn_exp2f(p0[r]); p1[r] = __builtin_amdgcn_exp2f(p1[r]); sum0 += p0[r]; sum1 += p1[r]; }
;     st.l += sum0 + sum1;
;     bf16x8 pf[4];
;     pf[0] = pack8(p0[0], p0[1], p0[2], p0[3], p0[4], p0[5], p0[6], p0[7]);
;     pf[1] = pack8(p0[8], p0[9], p0[10], p0[11], p0[12], p0[13], p0[14], p0[15]);
;     pf[2] = pack8(p1[0], p1[1], p1[2], p1[3], p1[4], p1[5], p1[6], p1[7]);
;     pf[3] = pack8(p1[8], p1[9], p1[10], p1[11], p1[12], p1[13], p1[14], p1[15]);
;     __builtin_amdgcn_sched_barrier(0);
; #pragma unroll
;     for (int db = 0; db < NDB; ++db) {
;         if (db + 1 < NDB) {
; #pragma unroll
;             for (int s4 = 0; s4 < 4; ++s4) { vlo[(db + 1) & 1][s4] = vtr(vp + (16 * s4) * PV + (db + 1) * 64); vhi[(db + 1) & 1][s4] = vtr(vp + (16 * s4 + 8) * PV + (db + 1) * 64); }
;         }
; #pragma unroll
;         for (int s4 = 0; s4 < 4; ++s4) {
;             const s16x4 lo = vlo[db & 1][s4], h4 = vhi[db & 1][s4];
;             const bf16x8 vb = {lo[0], lo[1], lo[2], lo[3], h4[0], h4[1], h4[2], h4[3]};
;             st.o[db] = __builtin_amdgcn_mfma_f32_32x32x16_bf16(pf[s4], vb, st.o[db], 0, 0, 0);
;         }
;         __builtin_amdgcn_sched_barrier(0);
;     }
.LBB0_601:
	v_exp_f32_e32 v165, v48
	v_exp_f32_e32 v164, v64
	v_exp_f32_e32 v167, v49
	v_exp_f32_e32 v166, v65
	v_exp_f32_e32 v65, v50
	v_exp_f32_e32 v64, v66
	v_exp_f32_e32 v169, v51
	v_exp_f32_e32 v168, v67
	v_pk_add_f32 v[48:49], v[164:165], 0 op_sel_hi:[1,0]
	v_exp_f32_e32 v67, v52
	v_exp_f32_e32 v66, v68
	v_pk_add_f32 v[48:49], v[166:167], v[48:49]
	v_exp_f32_e32 v171, v53
	v_exp_f32_e32 v170, v69
	v_pk_add_f32 v[48:49], v[64:65], v[48:49]
	v_exp_f32_e32 v69, v54
	v_exp_f32_e32 v68, v70
	v_pk_add_f32 v[48:49], v[168:169], v[48:49]
	v_exp_f32_e32 v173, v55
	v_exp_f32_e32 v172, v71
	v_exp_f32_e32 v71, v56
	v_exp_f32_e32 v70, v72
	v_pk_add_f32 v[48:49], v[66:67], v[48:49]
	v_exp_f32_e32 v175, v57
	v_exp_f32_e32 v174, v73
	v_pk_add_f32 v[48:49], v[170:171], v[48:49]
	v_exp_f32_e32 v73, v58
	v_exp_f32_e32 v72, v74
	v_pk_add_f32 v[48:49], v[68:69], v[48:49]
	v_exp_f32_e32 v177, v59
	v_exp_f32_e32 v176, v75
	v_pk_add_f32 v[48:49], v[172:173], v[48:49]
	v_exp_f32_e32 v75, v60
	v_exp_f32_e32 v74, v76
	v_pk_add_f32 v[48:49], v[70:71], v[48:49]
	v_exp_f32_e32 v179, v61
	v_exp_f32_e32 v178, v77
	v_pk_add_f32 v[48:49], v[174:175], v[48:49]
	v_exp_f32_e32 v77, v62
	v_exp_f32_e32 v76, v78
	v_pk_add_f32 v[48:49], v[72:73], v[48:49]
	v_exp_f32_e32 v181, v63
	v_exp_f32_e32 v180, v79
	v_pk_add_f32 v[48:49], v[176:177], v[48:49]
	v_cvt_pk_bf16_f32 v50, v67, v171
	v_pk_add_f32 v[48:49], v[74:75], v[48:49]
	v_cvt_pk_bf16_f32 v51, v69, v173
	v_pk_add_f32 v[48:49], v[178:179], v[48:49]
	v_cvt_pk_bf16_f32 v52, v71, v175
	v_pk_add_f32 v[48:49], v[76:77], v[48:49]
	v_cvt_pk_bf16_f32 v53, v73, v177
	v_pk_add_f32 v[48:49], v[180:181], v[48:49]
	v_cvt_pk_bf16_f32 v54, v75, v179
	v_add_f32_e32 v48, v48, v49
	v_add_f32_e32 v160, v160, v48
	v_cvt_pk_bf16_f32 v48, v165, v167
	v_cvt_pk_bf16_f32 v49, v65, v169
	v_cvt_pk_bf16_f32 v55, v77, v181
	v_cvt_pk_bf16_f32 v56, v164, v166
	v_cvt_pk_bf16_f32 v57, v64, v168
	v_cvt_pk_bf16_f32 v58, v66, v170
	v_cvt_pk_bf16_f32 v59, v68, v172
	v_cvt_pk_bf16_f32 v60, v70, v174
	v_cvt_pk_bf16_f32 v61, v72, v176
	v_cvt_pk_bf16_f32 v62, v74, v178
	v_cvt_pk_bf16_f32 v63, v76, v180
	ds_read_b64_tr_b16 v[64:65], v163 offset:21568
	ds_read_b64_tr_b16 v[66:67], v163 offset:23104
	ds_read_b64_tr_b16 v[68:69], v163 offset:24640
	ds_read_b64_tr_b16 v[70:71], v163 offset:26176
	ds_read_b64_tr_b16 v[72:73], v163 offset:27712
	ds_read_b64_tr_b16 v[74:75], v163 offset:29248
	ds_read_b64_tr_b16 v[76:77], v163 offset:30784
	ds_read_b64_tr_b16 v[78:79], v163 offset:32320
	s_waitcnt lgkmcnt(14)
	v_mfma_f32_32x32x16_bf16 v[16:31], v[48:51], v[140:143], v[16:31]
	s_waitcnt lgkmcnt(12)
	v_mfma_f32_32x32x16_bf16 v[16:31], v[52:55], v[136:139], v[16:31]
	s_waitcnt lgkmcnt(10)
	v_mfma_f32_32x32x16_bf16 v[16:31], v[56:59], v[132:135], v[16:31]
	s_waitcnt lgkmcnt(8)
	v_mfma_f32_32x32x16_bf16 v[16:31], v[60:63], v[128:131], v[16:31]
	s_waitcnt lgkmcnt(6)
	v_mfma_f32_32x32x16_bf16 v[0:15], v[48:51], v[64:67], v[0:15]
	s_waitcnt lgkmcnt(4)
	v_mfma_f32_32x32x16_bf16 v[0:15], v[52:55], v[68:71], v[0:15]
	s_waitcnt lgkmcnt(2)
	v_mfma_f32_32x32x16_bf16 v[0:15], v[56:59], v[72:75], v[0:15]
	s_waitcnt lgkmcnt(0)
	v_mfma_f32_32x32x16_bf16 v[0:15], v[60:63], v[76:79], v[0:15]
	s_waitcnt vmcnt(1)
	ds_write_b128 v156, v[108:111] offset:33792
	s_and_saveexec_b64 s[4:5], s[0:1]
	s_cbranch_execnz .LBB0_573
	s_branch .LBB0_574
